# adds: P0 dt-weight LDS table padded (bank-conflict-free ds_read_b128), P8 final rmsnorm loads all rows of a wave up front with counted waits
# speedup vs baseline: 1.0248x; 1.0097x over previous
.LBB0_20:
	v_mul_u32_u24_sdwa v12, v0, s2 dst_sel:DWORD dst_unused:UNUSED_PAD src0_sel:WORD_0 src1_sel:DWORD
	v_mul_u32_u24_sdwa v13, v1, s2 dst_sel:DWORD dst_unused:UNUSED_PAD src0_sel:WORD_0 src1_sel:DWORD
	v_lshrrev_b32_e32 v12, 19, v12
	v_lshrrev_b32_e32 v13, 19, v13
	v_perm_b32 v4, v1, v0, s1
	v_perm_b32 v14, v13, v12, s1
	v_pk_add_u16 v20, v4, s11 op_sel_hi:[1,0]
	v_pk_mul_lo_u16 v18, v14, 12 op_sel_hi:[1,0]
	v_and_b32_e32 v12, 0xffff, v12
	v_mul_u32_u24_sdwa v16, v20, s2 dst_sel:DWORD dst_unused:UNUSED_PAD src0_sel:WORD_0 src1_sel:DWORD
	v_mul_u32_u24_sdwa v17, v20, s2 dst_sel:DWORD dst_unused:UNUSED_PAD src0_sel:WORD_1 src1_sel:DWORD
	v_pk_sub_i16 v4, v4, v18
	v_and_b32_e32 v15, 0xffff, v13
	v_mad_u64_u32 v[12:13], s[12:13], v12, s3, v[2:3]
	v_lshrrev_b32_e32 v16, 19, v16
	v_lshrrev_b32_e32 v17, 19, v17
	v_alignbit_b32 v21, 0, v4, 16
	v_lshlrev_b32_sdwa v4, v11, v4 dst_sel:DWORD dst_unused:UNUSED_PAD src0_sel:DWORD src1_sel:WORD_0
	v_perm_b32 v18, v17, v16, s1
	v_lshl_add_u64 v[12:13], v[12:13], 0, v[4:5]
	v_mad_u64_u32 v[14:15], s[12:13], v15, s3, v[2:3]
	v_pk_mul_lo_u16 v22, v18, 12 op_sel_hi:[1,0]
	v_lshlrev_b32_e32 v4, 2, v21
	v_add_co_u32_e32 v12, vcc, s10, v12
	v_and_b32_e32 v16, 0xffff, v16
	v_pk_sub_i16 v20, v20, v22
	v_lshl_add_u64 v[14:15], v[14:15], 0, v[4:5]
	v_addc_co_u32_e32 v13, vcc, 0, v13, vcc
	v_and_b32_e32 v19, 0xffff, v17
	v_mad_u64_u32 v[16:17], s[12:13], v16, s3, v[2:3]
	v_alignbit_b32 v21, 0, v20, 16
	v_lshlrev_b32_sdwa v4, v11, v20 dst_sel:DWORD dst_unused:UNUSED_PAD src0_sel:DWORD src1_sel:WORD_0
	global_load_dword v20, v[12:13], off offset:3072
	v_add_co_u32_e32 v12, vcc, s10, v14
	v_mad_u64_u32 v[18:19], s[12:13], v19, s3, v[2:3]
	s_nop 0
	v_addc_co_u32_e32 v13, vcc, 0, v15, vcc
	v_lshl_add_u64 v[14:15], v[16:17], 0, v[4:5]
	v_lshlrev_b32_e32 v4, 2, v21
	v_add_co_u32_e32 v14, vcc, s10, v14
	v_lshl_add_u64 v[16:17], v[18:19], 0, v[4:5]
	s_nop 0
	v_addc_co_u32_e32 v15, vcc, 0, v15, vcc
	global_load_dword v4, v[12:13], off offset:3072
	global_load_dword v18, v[14:15], off offset:3072
	v_add_co_u32_e32 v12, vcc, s10, v16
	s_add_i32 s0, s0, 4
	s_nop 0
	v_addc_co_u32_e32 v13, vcc, 0, v17, vcc
	global_load_dword v12, v[12:13], off offset:3072
	v_cmp_eq_u32_e32 vcc, s0, v9
	v_add_u32_e32 v1, 0x800, v1
	v_add_u32_e32 v0, 0x800, v0
	s_or_b64 s[8:9], vcc, s[8:9]
	s_waitcnt vmcnt(2)
	v_mov_b32_e32 v118, v10
	v_lshrrev_b32_e32 v119, 6, v118
	v_mul_u32_u24_e32 v119, 0xaaab, v119
	v_lshrrev_b32_e32 v119, 17, v119
	v_lshl_add_u32 v118, v119, 4, v118
	ds_write_b32 v118, v20
	v_add_u32_e32 v118, 0x800, v10
	v_lshrrev_b32_e32 v119, 6, v118
	v_mul_u32_u24_e32 v119, 0xaaab, v119
	v_lshrrev_b32_e32 v119, 17, v119
	v_lshl_add_u32 v118, v119, 4, v118
	ds_write_b32 v118, v4
	s_waitcnt vmcnt(0)
	v_add_u32_e32 v118, 0x1000, v10
	v_lshrrev_b32_e32 v119, 6, v118
	v_mul_u32_u24_e32 v119, 0xaaab, v119
	v_lshrrev_b32_e32 v119, 17, v119
	v_lshl_add_u32 v118, v119, 4, v118
	ds_write_b32 v118, v18
	v_add_u32_e32 v118, 0x1800, v10
	v_lshrrev_b32_e32 v119, 6, v118
	v_mul_u32_u24_e32 v119, 0xaaab, v119
	v_lshrrev_b32_e32 v119, 17, v119
	v_lshl_add_u32 v118, v119, 4, v118
	ds_write_b32 v118, v12
	v_add_u32_e32 v10, 0x2000, v10
	s_andn2_b64 exec, exec, s[8:9]
	s_cbranch_execnz .LBB0_20
	s_or_b64 exec, exec, s[8:9]
	v_lshlrev_b32_e32 v2, 9, v9
.LBB0_22:
	s_or_b64 exec, exec, s[4:5]
	v_and_b32_e32 v3, 2, v8
	v_cmp_eq_u32_e32 vcc, 0, v3
	s_and_saveexec_b64 s[4:5], vcc
	s_cbranch_execz .LBB0_24
	s_mov_b32 s0, 0x5040100
	s_mov_b32 s1, 0xaaab
	v_perm_b32 v3, v1, v0, s0
	v_mul_u32_u24_sdwa v0, v0, s1 dst_sel:DWORD dst_unused:UNUSED_PAD src0_sel:WORD_0 src1_sel:DWORD
	v_mul_u32_u24_sdwa v1, v1, s1 dst_sel:DWORD dst_unused:UNUSED_PAD src0_sel:WORD_0 src1_sel:DWORD
	v_lshrrev_b32_e32 v0, 19, v0
	v_lshrrev_b32_e32 v1, 19, v1
	v_perm_b32 v4, v1, v0, s0
	v_and_b32_e32 v5, 0xffff, v0
	v_pk_mul_lo_u16 v0, v4, 12 op_sel_hi:[1,0]
	v_and_b32_e32 v8, 0xffff, v1
	v_pk_sub_i16 v3, v3, v0
	s_movk_i32 s2, 0x4c30
	s_waitcnt lgkmcnt(0)
	v_mov_b64_e32 v[0:1], s[6:7]
	v_mad_u64_u32 v[4:5], s[0:1], v5, s2, v[0:1]
	v_mad_u64_u32 v[0:1], s[0:1], v8, s2, v[0:1]
	v_mov_b32_e32 v8, 2
	v_lshlrev_b32_sdwa v8, v8, v3 dst_sel:DWORD dst_unused:UNUSED_PAD src0_sel:DWORD src1_sel:WORD_0
	v_mov_b32_e32 v9, 0
	v_alignbit_b32 v10, 0, v3, 16
	v_lshl_add_u64 v[4:5], v[4:5], 0, v[8:9]
	s_movk_i32 s0, 0x4000
	v_lshlrev_b32_e32 v8, 2, v10
	v_add_co_u32_e32 v4, vcc, s0, v4
	v_lshl_add_u64 v[0:1], v[0:1], 0, v[8:9]
	s_nop 0
	v_addc_co_u32_e32 v5, vcc, 0, v5, vcc
	v_add_co_u32_e32 v0, vcc, 0x4000, v0
	s_nop 1
	v_addc_co_u32_e32 v1, vcc, 0, v1, vcc
	global_load_dword v3, v[4:5], off offset:3072
	global_load_dword v8, v[0:1], off offset:3072
	v_or_b32_e32 v0, v194, v2
	v_lshl_add_u32 v0, v0, 2, 0
	s_waitcnt vmcnt(0)
	v_mov_b32_e32 v118, v0
	v_lshrrev_b32_e32 v119, 6, v118
	v_mul_u32_u24_e32 v119, 0xaaab, v119
	v_lshrrev_b32_e32 v119, 17, v119
	v_lshl_add_u32 v118, v119, 4, v118
	ds_write_b32 v118, v3
	v_add_u32_e32 v118, 0x800, v0
	v_lshrrev_b32_e32 v119, 6, v118
	v_mul_u32_u24_e32 v119, 0xaaab, v119
	v_lshrrev_b32_e32 v119, 17, v119
	v_lshl_add_u32 v118, v119, 4, v118
	ds_write_b32 v118, v8

.LBB0_26:
	v_mul_u32_u24_sdwa v2, v4, s0 dst_sel:DWORD dst_unused:UNUSED_PAD src0_sel:WORD_0 src1_sel:DWORD
	v_lshrrev_b32_e32 v2, 19, v2
	v_mul_lo_u16_e32 v8, 12, v2
	v_mad_u64_u32 v[6:7], s[10:11], v2, s1, v[0:1]
	v_sub_u16_e32 v2, v4, v8
	v_lshlrev_b32_e32 v2, 2, v2
	v_lshl_add_u64 v[6:7], v[6:7], 0, v[2:3]
	v_add_co_u32_e32 v6, vcc, 0x4000, v6
	s_nop 1
	v_addc_co_u32_e32 v7, vcc, 0, v7, vcc
	global_load_dword v2, v[6:7], off offset:3072
	v_add_u32_e32 v6, 0x200, v4
	v_cmp_lt_u32_e32 vcc, s2, v4
	s_or_b64 s[8:9], vcc, s[8:9]
	v_mov_b32_e32 v4, v6
	s_waitcnt vmcnt(0)
	v_mov_b32_e32 v118, v5
	v_lshrrev_b32_e32 v119, 6, v118
	v_mul_u32_u24_e32 v119, 0xaaab, v119
	v_lshrrev_b32_e32 v119, 17, v119
	v_lshl_add_u32 v118, v119, 4, v118
	ds_write_b32 v118, v2
	v_add_u32_e32 v5, 0x800, v5
	s_andn2_b64 exec, exec, s[8:9]
	s_cbranch_execnz .LBB0_26

.LBB0_30:
	s_or_b64 exec, exec, s[4:5]
	s_lshl_b32 s0, s97, 3
	s_add_i32 s42, s2, s0
	s_lshl_b32 s44, s96, 3
	s_cmpk_gt_i32 s42, 0x1cff
	s_cbranch_scc1 .LBB0_45
	v_readlane_b32 s0, v254, 2
	s_mulk_i32 s0, 0x2200
	v_lshrrev_b32_e32 v18, 5, v192
	v_and_b32_e32 v0, 31, v194
	s_add_i32 s2, s0, 0
	v_lshlrev_b32_e32 v16, 2, v0
	v_mul_u32_u24_e32 v0, 0x84, v18
	v_add3_u32 v31, s2, v16, v0
	v_lshlrev_b32_e32 v0, 3, v194
	v_and_b32_e32 v0, 56, v0
	v_mul_u32_u24_e32 v4, 0x84, v0
	v_lshlrev_b32_e32 v0, 1, v0
	v_mov_b32_e32 v1, 0
	v_lshrrev_b32_e32 v19, 3, v192
	v_lshl_add_u64 v[10:11], s[40:41], 0, v[0:1]
	s_mov_b64 s[0:1], 0x1790000
	v_lshl_add_u64 v[2:3], v[10:11], 0, s[0:1]
	v_lshlrev_b32_e32 v0, 2, v19
	s_mov_b64 s[0:1], 0xc90000
	v_readlane_b32 s10, v254, 3
	v_add3_u32 v0, s2, v4, v0
	v_lshl_add_u64 v[4:5], v[10:11], 0, s[0:1]
	s_mov_b64 s[0:1], 0x990000
	v_readlane_b32 s11, v254, 4
	v_lshl_add_u64 v[6:7], v[10:11], 0, s[0:1]
	s_load_dwordx2 s[8:9], s[10:11], 0x78
	s_load_dwordx4 s[0:3], s[10:11], 0x88
	v_mov_b32_e32 v17, v1
	s_waitcnt lgkmcnt(0)
	v_lshl_add_u64 v[8:9], s[6:7], 0, v[16:17]
	s_mov_b64 s[6:7], 0x10000
	s_mov_b32 s5, 0
	v_lshl_add_u64 v[12:13], s[2:3], 0, v[16:17]
	s_lshl_b32 s2, s42, 1
	v_or_b32_e32 v20, 8, v19
	v_or_b32_e32 v21, 16, v19
	v_or_b32_e32 v22, 24, v19
	v_bfe_u32 v23, v192, 3, 2
	v_lshl_add_u64 v[10:11], v[10:11], 0, s[6:7]
	v_lshl_add_u64 v[14:15], s[0:1], 0, v[16:17]
	v_lshl_add_u64 v[16:17], s[8:9], 0, v[16:17]
	s_lshl_b32 s0, s42, 5
	s_lshl_b32 s1, s44, 5
	s_add_i32 s2, s2, 0x1d100
	s_lshl_b32 s3, s44, 1
	s_mov_b32 s10, 0x16000
	s_mov_b32 s11, 0x2c000
	s_mov_b32 s12, 0xb000
	s_mov_b32 s13, 0x21000
	s_mov_b32 s14, 0x37000
	s_mov_b32 s15, 0x42000
	s_mov_b32 s16, 0x4d000
	s_mov_b32 s17, 0x58000
	s_mov_b32 s18, 0x63000
	s_mov_b32 s19, 0x6e000
	s_mov_b32 s20, 0x79000
	s_mov_b32 s21, 0x84000
	s_mov_b32 s22, 0x8f000
	s_mov_b32 s23, 0x9a000
	s_mov_b32 s24, 0xa5000
	s_mov_b32 s25, 0xb0000
	s_mov_b32 s26, 0xbb000
	s_mov_b32 s27, 0xc6000
	s_mov_b32 s28, 0xd1000
	s_mov_b32 s29, 0xdc000
	s_mov_b32 s30, 0xe7000
	s_mov_b32 s31, 0xf2000
	s_mov_b32 s33, 0xfd000
	s_mov_b32 s36, 0x108000
	s_mov_b32 s37, 0x113000
	s_mov_b32 s38, 0x11e000
	s_mov_b32 s39, 0x129000
	s_mov_b32 s43, 0x134000
	s_mov_b32 s45, 0x13f000
	s_mov_b32 s46, 0x14a000
	s_mov_b32 s47, 0x155000
	s_movk_i32 s48, 0x4c30
	v_add_u32_e32 v24, 0xd000, v31
	v_add_u32_e32 v25, 0xd400, v31
	v_add_u32_e32 v26, 0xd800, v31
	v_add_u32_e32 v27, 0xdc00, v31
	v_add_u32_e32 v28, 0xe000, v31
	v_add_u32_e32 v29, 0xe400, v31
	v_add_u32_e32 v30, 0xe800, v31
	v_add_u32_e32 v31, 0xec00, v31
	v_add_u32_e32 v32, 0xd000, v0
	s_mov_b32 s49, s42
	s_branch .LBB0_33

.LBB0_45:
	s_cmpk_lt_i32 s42, 0x4200
	s_waitcnt lgkmcnt(0)
	s_barrier
	s_cbranch_scc0 .LBB0_54
	v_readlane_b32 s6, v254, 3
	v_readlane_b32 s7, v254, 4
	s_load_dwordx4 s[36:39], s[6:7], 0x0
	s_load_dwordx2 s[0:1], s[6:7], 0x38
	s_add_i32 s2, s42, 0xffffc000
	s_ashr_i32 s43, s42, 31
	s_cmpk_lt_i32 s42, 0x4000
	s_cselect_b32 s3, s43, 0
	s_cselect_b32 s2, s42, s2
	s_waitcnt lgkmcnt(0)
	s_cselect_b32 s4, s37, s39
	s_cselect_b32 s5, s36, s38
	s_lshl_b64 s[2:3], s[2:3], 12
	s_add_u32 s2, s5, s2
	s_addc_u32 s3, s4, s3
	v_lshlrev_b32_e32 v0, 4, v192
	global_load_dwordx4 v[20:23], v0, s[2:3] offset:2048
	global_load_dwordx4 v[16:19], v0, s[2:3] offset:3072
	global_load_dwordx4 v[28:31], v0, s[2:3]
	global_load_dwordx4 v[24:27], v0, s[2:3] offset:1024
	v_mbcnt_lo_u32_b32 v2, -1, 0
	v_mbcnt_hi_u32_b32 v2, -1, v2
	v_and_b32_e32 v3, 64, v2
	v_add_u32_e32 v3, 64, v3
	v_xor_b32_e32 v4, 1, v2
	v_cmp_lt_i32_e32 vcc, v4, v3
	s_load_dwordx2 s[2:3], s[6:7], 0x58
	v_mov_b32_e32 v1, 0
	v_cndmask_b32_e32 v4, v2, v4, vcc
	v_lshlrev_b32_e32 v45, 2, v4
	v_xor_b32_e32 v4, 2, v2
	v_cmp_lt_i32_e32 vcc, v4, v3
	v_lshl_add_u64 v[34:35], s[0:1], 0, v[0:1]
	s_ashr_i32 s45, s44, 31
	v_cndmask_b32_e32 v4, v2, v4, vcc
	v_lshlrev_b32_e32 v46, 2, v4
	v_xor_b32_e32 v4, 4, v2
	v_cmp_lt_i32_e32 vcc, v4, v3
	v_cmp_eq_u32_e64 s[4:5], 11, v192
	v_cmp_eq_u32_e64 s[6:7], 10, v192
	v_cndmask_b32_e32 v4, v2, v4, vcc
	v_lshlrev_b32_e32 v47, 2, v4
	v_xor_b32_e32 v4, 8, v2
	v_cmp_lt_i32_e32 vcc, v4, v3
	v_cmp_eq_u32_e64 s[8:9], 9, v192
	v_cmp_eq_u32_e64 s[10:11], 8, v192
	v_cndmask_b32_e32 v4, v2, v4, vcc
	v_lshlrev_b32_e32 v48, 2, v4
	v_xor_b32_e32 v4, 16, v2
	v_cmp_lt_i32_e32 vcc, v4, v3
	v_cmp_eq_u32_e64 s[12:13], 7, v192
	v_cmp_eq_u32_e64 s[14:15], 6, v192
	v_cndmask_b32_e32 v4, v2, v4, vcc
	v_lshlrev_b32_e32 v49, 2, v4
	v_xor_b32_e32 v4, 32, v2
	v_cmp_lt_i32_e32 vcc, v4, v3
	v_mov_b32_e32 v3, v1
	v_cmp_eq_u32_e64 s[16:17], 5, v192
	v_cndmask_b32_e32 v2, v2, v4, vcc
	v_lshlrev_b32_e32 v50, 2, v2
	v_lshlrev_b32_e32 v2, 2, v192
	v_mad_i64_i32 v[0:1], s[0:1], s42, 48, v[2:3]
	s_mov_b64 s[0:1], 0x3e10000
	v_mul_u32_u24_e32 v4, 0xd0, v192
	v_lshl_add_u64 v[36:37], v[0:1], 0, s[0:1]
	s_lshl_b64 s[0:1], s[42:43], 11
	s_waitcnt lgkmcnt(0)
	v_lshl_add_u64 v[32:33], s[2:3], 0, v[2:3]
	v_lshl_or_b32 v38, v192, 3, s0
	s_add_i32 s0, s42, s44
	v_add_u32_e32 v53, 0, v4
	v_cmp_gt_u32_e32 vcc, 12, v192
	v_cmp_eq_u32_e64 s[18:19], 4, v192
	v_cmp_eq_u32_e64 s[20:21], 3, v192
	v_cmp_eq_u32_e64 s[22:23], 2, v192
	v_cmp_eq_u32_e64 s[24:25], 1, v192
	v_cmp_eq_u32_e64 s[26:27], 0, v192
	s_mul_hi_i32 s47, s44, 48
	s_mul_i32 s46, s44, 48
	v_mov_b32_e32 v39, s1
	s_lshl_b64 s[48:49], s[44:45], 11
	s_ashr_i32 s1, s0, 31
	v_lshlrev_b32_e32 v51, 4, v192
	v_mov_b32_e32 v52, 0x3727c5ac
	s_mov_b32 s2, 0x800000
	s_mov_b32 s3, 0x1d10000
	s_mov_b32 s33, 0x41a00000
	s_mov_b32 s43, 0x3f2aaaab
	v_mov_b32_e32 v54, 0x3ecc95a3
	s_mov_b32 s52, 0x3f317218
	s_mov_b32 s53, 0x7f800000
	s_mov_b32 s54, 0x33800000
	v_mov_b32_e32 v40, 0x3f317218
	v_mov_b32_e32 v55, 0x7f800000
	v_mov_b32_e32 v56, 0x7fc00000
	v_mov_b32_e32 v57, 0xff800000
	global_load_dwordx4 v[196:199], v[34:35], off
	global_load_dwordx4 v[200:203], v[34:35], off offset:1024
	global_load_dwordx4 v[204:207], v[34:35], off offset:2048
	global_load_dwordx4 v[208:211], v[34:35], off offset:3072
	s_waitcnt vmcnt(7)
	v_mov_b64_e32 v[4:5], v[20:21]
	s_waitcnt vmcnt(6)
	s_waitcnt vmcnt(2)
	v_mov_b64_e32 v[0:1], v[16:17]
	s_waitcnt vmcnt(1)
	v_mov_b64_e32 v[12:13], v[28:29]
	s_waitcnt vmcnt(0)
	v_mov_b64_e32 v[8:9], v[24:25]
	v_mov_b64_e32 v[2:3], v[18:19]
	v_mov_b64_e32 v[6:7], v[22:23]
	v_mov_b64_e32 v[10:11], v[26:27]
	v_mov_b64_e32 v[14:15], v[30:31]
	s_branch .LBB0_49

.LBB0_51:
	s_waitcnt lgkmcnt(0)
	v_mul_f32_e32 v41, v29, v29
	v_mul_f32_e32 v42, v31, v31
	v_mul_f32_e32 v43, v25, v25
	v_mul_f32_e32 v44, v27, v27
	v_mul_f32_e32 v62, v21, v21
	v_mul_f32_e32 v63, v23, v23
	v_fmac_f32_e32 v41, v28, v28
	v_fmac_f32_e32 v42, v30, v30
	v_fmac_f32_e32 v43, v24, v24
	v_fmac_f32_e32 v44, v26, v26
	v_mul_f32_e32 v64, v17, v17
	v_mul_f32_e32 v65, v19, v19
	v_fmac_f32_e32 v62, v20, v20
	v_fmac_f32_e32 v63, v22, v22
	v_add_f32_e32 v41, v41, v42
	v_add_f32_e32 v42, v43, v44
	v_fmac_f32_e32 v64, v16, v16
	v_fmac_f32_e32 v65, v18, v18
	v_add_f32_e32 v43, v62, v63
	v_add_f32_e32 v41, v42, v41
	v_add_f32_e32 v44, v64, v65
	v_add_f32_e32 v41, v43, v41
	v_add_f32_e32 v41, v44, v41
	ds_bpermute_b32 v42, v45, v41
	ds_read_b128 v[64:67], v53
	ds_read_b128 v[68:71], v53 offset:16
	ds_read_b128 v[72:75], v53 offset:32
	ds_read_b128 v[76:79], v53 offset:48
	ds_read_b128 v[80:83], v53 offset:64
	ds_read_b128 v[84:87], v53 offset:80
	s_waitcnt lgkmcnt(6)
	v_add_f32_e32 v41, v41, v42
	ds_bpermute_b32 v42, v46, v41
	s_waitcnt lgkmcnt(0)
	v_add_f32_e32 v41, v41, v42
	ds_bpermute_b32 v42, v47, v41
	s_waitcnt lgkmcnt(0)
	v_add_f32_e32 v41, v41, v42
	ds_bpermute_b32 v42, v48, v41
	s_waitcnt lgkmcnt(0)
	v_add_f32_e32 v41, v41, v42
	ds_bpermute_b32 v44, v49, v41
	v_lshl_add_u64 v[42:43], s[40:41], 0, v[38:39]
	v_add_co_u32_e64 v42, s[30:31], s3, v42
	s_waitcnt lgkmcnt(0)
	v_add_f32_e32 v41, v41, v44
	ds_bpermute_b32 v44, v50, v41
	v_addc_co_u32_e64 v43, s[30:31], 0, v43, s[30:31]
	s_waitcnt lgkmcnt(0)
	v_add_f32_e32 v41, v41, v44
	v_fmamk_f32 v41, v41, 0x3a800000, v52
	v_mul_f32_e32 v44, 0x4b800000, v41
	v_cmp_gt_f32_e64 s[28:29], s2, v41
	s_nop 1
	v_cndmask_b32_e64 v41, v41, v44, s[28:29]
	v_rsq_f32_e32 v41, v41
	s_nop 0
	v_mul_f32_e32 v44, 0x45800000, v41
	v_cndmask_b32_e64 v44, v41, v44, s[28:29]
	v_pk_mul_f32 v[28:29], v[28:29], v[44:45] op_sel_hi:[1,0]
	v_pk_mul_f32 v[30:31], v[30:31], v[44:45] op_sel_hi:[1,0]
	v_pk_mul_f32 v[90:91], v[196:197], v[28:29]
	v_pk_mul_f32 v[88:89], v[198:199], v[30:31]
	v_cvt_pk_bf16_f32 v92, v90, v91
	v_cvt_pk_bf16_f32 v93, v88, v89
	v_fma_f32 v63, v64, v90, 0
	v_fma_f32 v64, v65, v90, 0
	global_store_dwordx2 v[42:43], v[92:93], off
	v_fma_f32 v62, v66, v90, 0
	v_fma_f32 v61, v67, v90, 0
	v_fma_f32 v60, v68, v90, 0
	v_fma_f32 v59, v69, v90, 0
	v_fma_f32 v58, v70, v90, 0
	v_fma_f32 v41, v71, v90, 0
	v_fma_f32 v31, v72, v90, 0
	v_fma_f32 v30, v73, v90, 0
	v_fma_f32 v29, v74, v90, 0
	v_fma_f32 v28, v75, v90, 0
	v_fmac_f32_e32 v63, v76, v91
	v_fmac_f32_e32 v64, v77, v91
	ds_read_b128 v[66:69], v53 offset:96
	ds_read_b128 v[70:73], v53 offset:112
	ds_read_b128 v[74:77], v53 offset:128
	v_fmac_f32_e32 v62, v78, v91
	v_fmac_f32_e32 v61, v79, v91
	v_fmac_f32_e32 v60, v80, v91
	v_fmac_f32_e32 v59, v81, v91
	v_fmac_f32_e32 v58, v82, v91
	v_fmac_f32_e32 v41, v83, v91
	v_fmac_f32_e32 v31, v84, v91
	v_fmac_f32_e32 v30, v85, v91
	v_fmac_f32_e32 v29, v86, v91
	v_fmac_f32_e32 v28, v87, v91
	s_waitcnt lgkmcnt(2)
	v_fmac_f32_e32 v63, v66, v88
	v_fmac_f32_e32 v64, v67, v88
	v_fmac_f32_e32 v62, v68, v88
	v_fmac_f32_e32 v61, v69, v88
	s_waitcnt lgkmcnt(1)
	v_fmac_f32_e32 v60, v70, v88
	v_fmac_f32_e32 v59, v71, v88
	v_fmac_f32_e32 v58, v72, v88
	v_fmac_f32_e32 v41, v73, v88
	ds_read_b128 v[66:69], v53 offset:144
	s_waitcnt lgkmcnt(1)
	v_fmac_f32_e32 v31, v74, v88
	v_fmac_f32_e32 v30, v75, v88
	v_fmac_f32_e32 v29, v76, v88
	v_fmac_f32_e32 v28, v77, v88
	ds_read_b128 v[70:73], v53 offset:160
	ds_read_b128 v[74:77], v53 offset:176
	s_waitcnt lgkmcnt(2)
	v_fmac_f32_e32 v61, v69, v89
	v_fmac_f32_e32 v63, v66, v89
	v_fmac_f32_e32 v64, v67, v89
	s_waitcnt lgkmcnt(1)
	v_fmac_f32_e32 v60, v89, v70
	v_fmac_f32_e32 v59, v89, v71
	v_fmac_f32_e32 v58, v89, v72
	v_fmac_f32_e32 v41, v89, v73
	s_waitcnt lgkmcnt(0)
	v_fmac_f32_e32 v31, v89, v74
	v_fmac_f32_e32 v30, v89, v75
	v_fmac_f32_e32 v29, v89, v76
	v_fmac_f32_e32 v28, v89, v77
	v_fmac_f32_e32 v62, v68, v89
	v_pk_mul_f32 v[114:115], v[24:25], v[44:45] op_sel_hi:[1,0]
	v_pk_mul_f32 v[116:117], v[26:27], v[44:45] op_sel_hi:[1,0]
	ds_read_b128 v[24:27], v53 offset:13312
	ds_read_b128 v[70:73], v53 offset:13328
	ds_read_b128 v[74:77], v53 offset:13344
	ds_read_b128 v[78:81], v53 offset:13360
	ds_read_b128 v[82:85], v53 offset:13376
	ds_read_b128 v[86:89], v53 offset:13392
	ds_read_b128 v[90:93], v53 offset:13408
	ds_read_b128 v[94:97], v53 offset:13424
	ds_read_b128 v[98:101], v53 offset:13440
	ds_read_b128 v[102:105], v53 offset:13456
	ds_read_b128 v[106:109], v53 offset:13472
	ds_read_b128 v[110:113], v53 offset:13488
	v_pk_mul_f32 v[66:67], v[114:115], v[200:201]
	s_waitcnt lgkmcnt(11)
	v_fmac_f32_e32 v61, v66, v27
	s_waitcnt lgkmcnt(10)
	v_fmac_f32_e32 v60, v66, v70
	v_fmac_f32_e32 v59, v66, v71
	v_fmac_f32_e32 v58, v66, v72
	v_fmac_f32_e32 v41, v66, v73
	s_waitcnt lgkmcnt(9)
	v_fmac_f32_e32 v31, v66, v74
	v_fmac_f32_e32 v30, v66, v75
	v_fmac_f32_e32 v29, v66, v76
	v_fmac_f32_e32 v28, v66, v77
	v_pk_mul_f32 v[68:69], v[116:117], v[202:203]
	v_fmac_f32_e32 v63, v66, v24
	v_fmac_f32_e32 v64, v66, v25
	v_fmac_f32_e32 v62, v66, v26
	s_waitcnt lgkmcnt(8)
	v_fmac_f32_e32 v61, v67, v81
	s_waitcnt lgkmcnt(7)
	v_fmac_f32_e32 v60, v67, v82
	v_fmac_f32_e32 v59, v67, v83
	v_fmac_f32_e32 v58, v67, v84
	v_fmac_f32_e32 v41, v67, v85
	s_waitcnt lgkmcnt(6)
	v_fmac_f32_e32 v31, v67, v86
	v_fmac_f32_e32 v30, v67, v87
	v_fmac_f32_e32 v29, v67, v88
	v_fmac_f32_e32 v28, v67, v89
	v_fmac_f32_e32 v63, v67, v78
	v_fmac_f32_e32 v64, v67, v79
	v_fmac_f32_e32 v62, v67, v80
	s_waitcnt lgkmcnt(5)
	v_fmac_f32_e32 v61, v68, v93
	s_waitcnt lgkmcnt(4)
	v_fmac_f32_e32 v60, v68, v94
	v_fmac_f32_e32 v59, v68, v95
	v_fmac_f32_e32 v58, v68, v96
	v_fmac_f32_e32 v41, v68, v97
	s_waitcnt lgkmcnt(3)
	v_fmac_f32_e32 v31, v68, v98
	v_fmac_f32_e32 v30, v68, v99
	v_fmac_f32_e32 v29, v68, v100
	v_fmac_f32_e32 v28, v68, v101
	v_cvt_pk_bf16_f32 v114, v66, v67
	v_cvt_pk_bf16_f32 v115, v68, v69
	v_fmac_f32_e32 v63, v68, v90
	v_fmac_f32_e32 v64, v68, v91
	v_fmac_f32_e32 v62, v68, v92
	s_waitcnt lgkmcnt(2)
	v_fmac_f32_e32 v61, v69, v105
	s_waitcnt lgkmcnt(1)
	v_fmac_f32_e32 v60, v69, v106
	v_fmac_f32_e32 v59, v69, v107
	v_fmac_f32_e32 v58, v69, v108
	v_fmac_f32_e32 v41, v69, v109
	s_waitcnt lgkmcnt(0)
	v_fmac_f32_e32 v31, v69, v110
	v_fmac_f32_e32 v30, v69, v111
	v_fmac_f32_e32 v29, v69, v112
	v_fmac_f32_e32 v28, v69, v113
	global_store_dwordx2 v[42:43], v[114:115], off offset:512
	v_fmac_f32_e32 v63, v69, v102
	v_fmac_f32_e32 v64, v69, v103
	v_fmac_f32_e32 v62, v69, v104
	v_pk_mul_f32 v[110:111], v[20:21], v[44:45] op_sel_hi:[1,0]
	v_pk_mul_f32 v[112:113], v[22:23], v[44:45] op_sel_hi:[1,0]
	ds_read_b128 v[20:23], v53 offset:26624
	ds_read_b128 v[66:69], v53 offset:26640
	ds_read_b128 v[70:73], v53 offset:26656
	ds_read_b128 v[74:77], v53 offset:26672
	ds_read_b128 v[78:81], v53 offset:26688
	ds_read_b128 v[82:85], v53 offset:26704
	ds_read_b128 v[86:89], v53 offset:26720
	ds_read_b128 v[90:93], v53 offset:26736
	ds_read_b128 v[94:97], v53 offset:26752
	ds_read_b128 v[98:101], v53 offset:26768
	ds_read_b128 v[102:105], v53 offset:26784
	ds_read_b128 v[106:109], v53 offset:26800
	v_pk_mul_f32 v[24:25], v[110:111], v[204:205]
	s_waitcnt lgkmcnt(11)
	v_fmac_f32_e32 v61, v24, v23
	s_waitcnt lgkmcnt(10)
	v_fmac_f32_e32 v60, v24, v66
	v_fmac_f32_e32 v59, v24, v67
	v_fmac_f32_e32 v58, v24, v68
	v_fmac_f32_e32 v41, v24, v69
	s_waitcnt lgkmcnt(9)
	v_fmac_f32_e32 v31, v24, v70
	v_fmac_f32_e32 v30, v24, v71
	v_fmac_f32_e32 v29, v24, v72
	v_fmac_f32_e32 v28, v24, v73
	v_pk_mul_f32 v[26:27], v[112:113], v[206:207]
	v_fmac_f32_e32 v63, v24, v20
	v_fmac_f32_e32 v64, v24, v21
	v_fmac_f32_e32 v62, v24, v22
	s_waitcnt lgkmcnt(8)
	v_fmac_f32_e32 v61, v25, v77
	s_waitcnt lgkmcnt(7)
	v_fmac_f32_e32 v60, v25, v78
	v_fmac_f32_e32 v59, v25, v79
	v_fmac_f32_e32 v58, v25, v80
	v_fmac_f32_e32 v41, v25, v81
	s_waitcnt lgkmcnt(6)
	v_fmac_f32_e32 v31, v25, v82
	v_fmac_f32_e32 v30, v25, v83
	v_fmac_f32_e32 v29, v25, v84
	v_fmac_f32_e32 v28, v25, v85
	v_fmac_f32_e32 v63, v25, v74
	v_fmac_f32_e32 v64, v25, v75
	v_fmac_f32_e32 v62, v25, v76
	s_waitcnt lgkmcnt(5)
	v_fmac_f32_e32 v61, v26, v89
	s_waitcnt lgkmcnt(4)
	v_fmac_f32_e32 v60, v26, v90
	v_fmac_f32_e32 v59, v26, v91
	v_fmac_f32_e32 v58, v26, v92
	v_fmac_f32_e32 v41, v26, v93
	s_waitcnt lgkmcnt(3)
	v_fmac_f32_e32 v31, v26, v94
	v_fmac_f32_e32 v30, v26, v95
	v_fmac_f32_e32 v29, v26, v96
	v_fmac_f32_e32 v28, v26, v97
	v_cvt_pk_bf16_f32 v110, v24, v25
	v_cvt_pk_bf16_f32 v111, v26, v27
	v_fmac_f32_e32 v63, v26, v86
	v_fmac_f32_e32 v64, v26, v87
	v_fmac_f32_e32 v62, v26, v88
	s_waitcnt lgkmcnt(2)
	v_fmac_f32_e32 v61, v27, v101
	s_waitcnt lgkmcnt(1)
	v_fmac_f32_e32 v60, v27, v102
	v_fmac_f32_e32 v59, v27, v103
	v_fmac_f32_e32 v58, v27, v104
	v_fmac_f32_e32 v41, v27, v105
	s_waitcnt lgkmcnt(0)
	v_fmac_f32_e32 v31, v27, v106
	v_fmac_f32_e32 v30, v27, v107
	v_fmac_f32_e32 v29, v27, v108
	v_fmac_f32_e32 v28, v27, v109
	global_store_dwordx2 v[42:43], v[110:111], off offset:1024
	v_fmac_f32_e32 v63, v27, v98
	v_fmac_f32_e32 v64, v27, v99
	v_fmac_f32_e32 v62, v27, v100
	v_pk_mul_f32 v[106:107], v[16:17], v[44:45] op_sel_hi:[1,0]
	v_pk_mul_f32 v[108:109], v[18:19], v[44:45] op_sel_hi:[1,0]
	ds_read_b128 v[16:19], v53 offset:39936
	ds_read_b128 v[24:27], v53 offset:39952
	ds_read_b128 v[66:69], v53 offset:39968
	ds_read_b128 v[70:73], v53 offset:39984
	ds_read_b128 v[74:77], v53 offset:40000
	ds_read_b128 v[78:81], v53 offset:40016
	ds_read_b128 v[82:85], v53 offset:40032
	ds_read_b128 v[86:89], v53 offset:40048
	ds_read_b128 v[90:93], v53 offset:40064
	ds_read_b128 v[94:97], v53 offset:40080
	ds_read_b128 v[98:101], v53 offset:40096
	ds_read_b128 v[102:105], v53 offset:40112
	v_pk_mul_f32 v[20:21], v[106:107], v[208:209]
	s_waitcnt lgkmcnt(11)
	v_fmac_f32_e32 v61, v20, v19
	s_waitcnt lgkmcnt(10)
	v_fmac_f32_e32 v60, v20, v24
	v_fmac_f32_e32 v59, v20, v25
	v_fmac_f32_e32 v58, v20, v26
	v_fmac_f32_e32 v41, v20, v27
	s_waitcnt lgkmcnt(9)
	v_fmac_f32_e32 v31, v20, v66
	v_fmac_f32_e32 v30, v20, v67
	v_fmac_f32_e32 v29, v20, v68
	v_fmac_f32_e32 v28, v20, v69
	v_pk_mul_f32 v[22:23], v[108:109], v[210:211]
	v_fmac_f32_e32 v63, v20, v16
	v_fmac_f32_e32 v64, v20, v17
	v_fmac_f32_e32 v62, v20, v18
	s_waitcnt lgkmcnt(8)
	v_fmac_f32_e32 v61, v21, v73
	s_waitcnt lgkmcnt(7)
	v_fmac_f32_e32 v60, v21, v74
	v_fmac_f32_e32 v59, v21, v75
	v_fmac_f32_e32 v58, v21, v76
	v_fmac_f32_e32 v41, v21, v77
	s_waitcnt lgkmcnt(6)
	v_fmac_f32_e32 v31, v21, v78
	v_fmac_f32_e32 v30, v21, v79
	v_fmac_f32_e32 v29, v21, v80
	v_fmac_f32_e32 v28, v21, v81
	v_fmac_f32_e32 v63, v21, v70
	v_fmac_f32_e32 v64, v21, v71
	v_fmac_f32_e32 v62, v21, v72
	s_waitcnt lgkmcnt(5)
	v_fmac_f32_e32 v61, v22, v85
	s_waitcnt lgkmcnt(4)
	v_fmac_f32_e32 v60, v22, v86
	v_fmac_f32_e32 v59, v22, v87
	v_fmac_f32_e32 v58, v22, v88
	v_fmac_f32_e32 v41, v22, v89
	s_waitcnt lgkmcnt(3)
	v_fmac_f32_e32 v31, v22, v90
	v_fmac_f32_e32 v30, v22, v91
	v_fmac_f32_e32 v29, v22, v92
	v_fmac_f32_e32 v28, v22, v93
	v_cvt_pk_bf16_f32 v106, v20, v21
	v_cvt_pk_bf16_f32 v107, v22, v23
	v_fmac_f32_e32 v63, v22, v82
	v_fmac_f32_e32 v64, v22, v83
	v_fmac_f32_e32 v62, v22, v84
	s_waitcnt lgkmcnt(2)
	v_fmac_f32_e32 v61, v23, v97
	s_waitcnt lgkmcnt(1)
	v_fmac_f32_e32 v60, v23, v98
	v_fmac_f32_e32 v59, v23, v99
	v_fmac_f32_e32 v58, v23, v100
	v_fmac_f32_e32 v41, v23, v101
	s_waitcnt lgkmcnt(0)
	v_fmac_f32_e32 v31, v23, v102
	v_fmac_f32_e32 v30, v23, v103
	v_fmac_f32_e32 v29, v23, v104
	v_fmac_f32_e32 v28, v23, v105
	global_store_dwordx2 v[42:43], v[106:107], off offset:1536
	v_fmac_f32_e32 v63, v23, v94
	v_fmac_f32_e32 v64, v23, v95
	v_fmac_f32_e32 v62, v23, v96
	ds_bpermute_b32 v20, v45, v62
	ds_bpermute_b32 v21, v45, v61
	ds_bpermute_b32 v44, v45, v31
	ds_bpermute_b32 v24, v45, v60
	ds_bpermute_b32 v16, v45, v63
	s_waitcnt lgkmcnt(4)
	v_add_f32_e32 v20, v62, v20
	ds_bpermute_b32 v22, v46, v20
	s_waitcnt lgkmcnt(4)
	v_add_f32_e32 v21, v61, v21
	ds_bpermute_b32 v23, v46, v21
	s_waitcnt lgkmcnt(4)
	v_add_f32_e32 v31, v31, v44
	s_waitcnt lgkmcnt(3)
	v_add_f32_e32 v24, v60, v24
	s_waitcnt lgkmcnt(1)
	v_add_f32_e32 v20, v20, v22
	ds_bpermute_b32 v22, v47, v20
	s_waitcnt lgkmcnt(1)
	v_add_f32_e32 v21, v21, v23
	ds_bpermute_b32 v23, v47, v21
	ds_bpermute_b32 v17, v45, v64
	ds_bpermute_b32 v61, v45, v28
	s_waitcnt lgkmcnt(3)
	v_add_f32_e32 v20, v20, v22
	ds_bpermute_b32 v22, v48, v20
	s_waitcnt lgkmcnt(3)
	v_add_f32_e32 v21, v21, v23
	ds_bpermute_b32 v23, v48, v21
	v_add_f32_e32 v16, v63, v16
	s_waitcnt lgkmcnt(3)
	v_add_f32_e32 v17, v64, v17
	s_waitcnt lgkmcnt(1)
	v_add_f32_e32 v20, v20, v22
	ds_bpermute_b32 v22, v49, v20
	s_waitcnt lgkmcnt(1)
	v_add_f32_e32 v23, v21, v23
	ds_bpermute_b32 v26, v49, v23
	v_add_f32_e32 v28, v28, v61
	ds_bpermute_b32 v18, v46, v16
	s_waitcnt lgkmcnt(2)
	v_add_f32_e32 v20, v20, v22
	ds_bpermute_b32 v22, v45, v59
	ds_bpermute_b32 v19, v46, v17
	ds_bpermute_b32 v25, v46, v24
	ds_bpermute_b32 v61, v46, v28
	s_waitcnt lgkmcnt(4)
	v_add_f32_e32 v16, v16, v18
	s_waitcnt lgkmcnt(3)
	v_add_f32_e32 v27, v59, v22
	ds_bpermute_b32 v42, v46, v27
	v_add_f32_e32 v22, v23, v26
	s_waitcnt lgkmcnt(3)
	v_add_f32_e32 v17, v17, v19
	s_waitcnt lgkmcnt(2)
	v_add_f32_e32 v24, v24, v25
	s_waitcnt lgkmcnt(1)
	v_add_f32_e32 v28, v28, v61
	s_waitcnt lgkmcnt(0)
	v_add_f32_e32 v26, v27, v42
	ds_bpermute_b32 v27, v47, v26
	ds_bpermute_b32 v42, v45, v58
	ds_bpermute_b32 v18, v47, v16
	ds_bpermute_b32 v19, v47, v17
	ds_bpermute_b32 v25, v47, v24
	s_waitcnt lgkmcnt(4)
	v_add_f32_e32 v26, v26, v27
	s_waitcnt lgkmcnt(3)
	v_add_f32_e32 v42, v58, v42
	ds_bpermute_b32 v27, v48, v26
	ds_bpermute_b32 v43, v46, v42
	ds_bpermute_b32 v61, v47, v28
	s_waitcnt lgkmcnt(5)
	v_add_f32_e32 v16, v16, v18
	s_waitcnt lgkmcnt(4)
	v_add_f32_e32 v17, v17, v19
	s_waitcnt lgkmcnt(2)
	v_add_f32_e32 v26, v26, v27
	ds_bpermute_b32 v27, v45, v41
	s_waitcnt lgkmcnt(2)
	v_add_f32_e32 v42, v42, v43
	ds_bpermute_b32 v43, v47, v42
	ds_bpermute_b32 v58, v49, v26
	v_add_f32_e32 v24, v24, v25
	s_waitcnt lgkmcnt(2)
	v_add_f32_e32 v27, v41, v27
	ds_bpermute_b32 v41, v46, v27
	s_waitcnt lgkmcnt(2)
	v_add_f32_e32 v42, v42, v43
	ds_bpermute_b32 v43, v46, v31
	ds_bpermute_b32 v44, v48, v42
	s_waitcnt lgkmcnt(3)
	v_add_f32_e32 v26, v26, v58
	s_waitcnt lgkmcnt(2)
	v_add_f32_e32 v27, v27, v41
	ds_bpermute_b32 v41, v47, v27
	s_waitcnt lgkmcnt(2)
	v_add_f32_e32 v31, v31, v43
	ds_bpermute_b32 v43, v47, v31
	s_waitcnt lgkmcnt(2)
	v_add_f32_e32 v42, v42, v44
	ds_bpermute_b32 v58, v49, v42
	s_waitcnt lgkmcnt(2)
	v_add_f32_e32 v41, v27, v41
	ds_bpermute_b32 v44, v48, v41
	s_waitcnt lgkmcnt(2)
	v_add_f32_e32 v43, v31, v43
	ds_bpermute_b32 v59, v48, v43
	s_waitcnt lgkmcnt(2)
	v_add_f32_e32 v31, v42, v58
	v_add_f32_e32 v28, v28, v61
	s_waitcnt lgkmcnt(1)
	v_add_f32_e32 v44, v41, v44
	ds_bpermute_b32 v60, v49, v44
	s_waitcnt lgkmcnt(1)
	v_add_f32_e32 v58, v43, v59
	ds_bpermute_b32 v59, v49, v58
	ds_bpermute_b32 v18, v48, v16
	ds_bpermute_b32 v19, v48, v17
	s_waitcnt lgkmcnt(3)
	v_add_f32_e32 v42, v44, v60
	ds_bpermute_b32 v60, v45, v30
	s_waitcnt lgkmcnt(3)
	v_add_f32_e32 v44, v58, v59
	ds_bpermute_b32 v59, v45, v29
	ds_bpermute_b32 v25, v48, v24
	ds_bpermute_b32 v61, v48, v28
	s_waitcnt lgkmcnt(3)
	v_add_f32_e32 v30, v30, v60
	ds_bpermute_b32 v60, v46, v30
	s_waitcnt lgkmcnt(3)
	v_add_f32_e32 v29, v29, v59
	ds_bpermute_b32 v59, v46, v29
	v_add_f32_e32 v16, v16, v18
	v_add_f32_e32 v17, v17, v19
	s_waitcnt lgkmcnt(1)
	v_add_f32_e32 v30, v30, v60
	ds_bpermute_b32 v60, v47, v30
	s_waitcnt lgkmcnt(1)
	v_add_f32_e32 v29, v29, v59
	ds_bpermute_b32 v59, v47, v29
	v_add_f32_e32 v24, v24, v25
	v_add_f32_e32 v61, v28, v61
	s_waitcnt lgkmcnt(1)
	v_add_f32_e32 v30, v30, v60
	ds_bpermute_b32 v60, v48, v30
	s_waitcnt lgkmcnt(1)
	v_add_f32_e32 v29, v29, v59
	ds_bpermute_b32 v59, v48, v29
	ds_bpermute_b32 v18, v49, v16
	ds_bpermute_b32 v19, v49, v17
	s_waitcnt lgkmcnt(3)
	v_add_f32_e32 v30, v30, v60
	ds_bpermute_b32 v25, v49, v24
	s_waitcnt lgkmcnt(3)
	v_add_f32_e32 v59, v29, v59
	ds_bpermute_b32 v60, v49, v30
	ds_bpermute_b32 v62, v49, v59
	ds_bpermute_b32 v63, v49, v61
	s_waitcnt lgkmcnt(5)
	v_add_f32_e32 v16, v16, v18
	s_waitcnt lgkmcnt(4)
	v_add_f32_e32 v18, v17, v19
	s_waitcnt lgkmcnt(3)
	v_add_f32_e32 v24, v24, v25
	s_waitcnt lgkmcnt(2)
	v_add_f32_e32 v28, v30, v60
	s_waitcnt lgkmcnt(1)
	v_add_f32_e32 v30, v59, v62
	s_waitcnt lgkmcnt(0)
	v_add_f32_e32 v60, v61, v63
	ds_bpermute_b32 v17, v50, v16
	ds_bpermute_b32 v19, v50, v18
	ds_bpermute_b32 v21, v50, v20
	ds_bpermute_b32 v23, v50, v22
	ds_bpermute_b32 v25, v50, v24
	ds_bpermute_b32 v27, v50, v26
	ds_bpermute_b32 v41, v50, v31
	ds_bpermute_b32 v43, v50, v42
	ds_bpermute_b32 v58, v50, v44
	ds_bpermute_b32 v29, v50, v28
	ds_bpermute_b32 v59, v50, v30
	ds_bpermute_b32 v61, v50, v60
	s_and_saveexec_b64 s[30:31], vcc
	s_cbranch_execz .LBB0_48
	global_load_dword v62, v[32:33], off
	s_waitcnt lgkmcnt(11)
	v_add_f32_e32 v16, v16, v17
	s_waitcnt lgkmcnt(10)
	v_add_f32_e32 v18, v18, v19
	v_cndmask_b32_e64 v16, 0, v16, s[26:27]
	s_waitcnt lgkmcnt(9)
	v_add_f32_e32 v20, v20, v21
	v_cndmask_b32_e64 v16, v16, v18, s[24:25]
	s_waitcnt lgkmcnt(8)
	v_add_f32_e32 v22, v22, v23
	v_cndmask_b32_e64 v16, v16, v20, s[22:23]
	s_waitcnt lgkmcnt(7)
	v_add_f32_e32 v24, v24, v25
	v_cndmask_b32_e64 v16, v16, v22, s[20:21]
	s_waitcnt lgkmcnt(6)
	v_add_f32_e32 v26, v26, v27
	v_cndmask_b32_e64 v16, v16, v24, s[18:19]
	s_waitcnt lgkmcnt(5)
	v_add_f32_e32 v31, v31, v41
	v_cndmask_b32_e64 v16, v16, v26, s[16:17]
	s_waitcnt lgkmcnt(4)
	v_add_f32_e32 v42, v42, v43
	v_cndmask_b32_e64 v16, v16, v31, s[14:15]
	s_waitcnt lgkmcnt(2)
	v_add_f32_e32 v28, v28, v29
	v_add_f32_e32 v29, v44, v58
	v_cndmask_b32_e64 v16, v16, v42, s[12:13]
	v_cndmask_b32_e64 v16, v16, v29, s[10:11]
	s_waitcnt lgkmcnt(1)
	v_add_f32_e32 v30, v30, v59
	v_cndmask_b32_e64 v16, v16, v28, s[8:9]
	s_waitcnt lgkmcnt(0)
	v_add_f32_e32 v60, v60, v61
	v_cndmask_b32_e64 v16, v16, v30, s[6:7]
	v_cndmask_b32_e64 v16, v16, v60, s[4:5]
	s_waitcnt vmcnt(0)
	v_add_f32_e32 v16, v16, v62
	v_cmp_nlt_f32_e64 s[28:29], s33, v16
	s_and_saveexec_b64 s[50:51], s[28:29]
	s_cbranch_execz .LBB0_47
	v_mul_f32_e32 v16, 0x3fb8aa3b, v16
	v_exp_f32_e32 v30, v16
	s_nop 0
	v_add_f32_e32 v18, 1.0, v30
	v_frexp_mant_f32_e32 v20, v18
	v_cvt_f64_f32_e32 v[16:17], v18
	v_frexp_exp_i32_f64_e32 v16, v[16:17]
	v_cmp_gt_f32_e64 s[28:29], s43, v20
	v_add_f32_e32 v19, -1.0, v18
	v_sub_f32_e32 v21, v19, v18
	v_subbrev_co_u32_e64 v24, s[28:29], 0, v16, s[28:29]
	v_sub_u32_e32 v16, 0, v24
	v_sub_f32_e32 v19, v30, v19
	v_add_f32_e32 v21, 1.0, v21
	v_ldexp_f32 v17, v18, v16
	v_add_f32_e32 v19, v19, v21
	v_add_f32_e32 v18, -1.0, v17
	v_add_f32_e32 v20, 1.0, v17
	v_ldexp_f32 v16, v19, v16
	v_add_f32_e32 v19, 1.0, v18
	v_add_f32_e32 v21, -1.0, v20
	v_sub_f32_e32 v19, v17, v19
	v_sub_f32_e32 v17, v17, v21
	v_add_f32_e32 v19, v16, v19
	v_add_f32_e32 v16, v16, v17
	v_add_f32_e32 v25, v20, v16
	v_rcp_f32_e32 v27, v25
	v_sub_f32_e32 v17, v25, v20
	v_sub_f32_e32 v26, v16, v17
	v_add_f32_e32 v17, v18, v19
	v_mul_f32_e32 v29, v17, v27
	v_sub_f32_e32 v16, v17, v18
	v_mul_f32_e32 v18, v25, v29
	v_fma_f32 v20, v29, v25, -v18
	v_fmac_f32_e32 v20, v29, v26
	v_sub_f32_e32 v28, v19, v16
	v_add_f32_e32 v16, v18, v20
	v_sub_f32_e32 v19, v17, v16
	v_pk_add_f32 v[22:23], v[16:17], v[18:19] neg_lo:[0,1] neg_hi:[0,1]
	v_mov_b32_e32 v21, v16
	v_pk_add_f32 v[16:17], v[22:23], v[20:21] neg_lo:[0,1] neg_hi:[0,1]
	v_cmp_neq_f32_e64 s[28:29], s53, v30
	v_add_f32_e32 v17, v28, v17
	v_add_f32_e32 v16, v16, v17
	v_add_f32_e32 v17, v19, v16
	v_mul_f32_e32 v28, v27, v17
	v_mul_f32_e32 v18, v25, v28
	v_fma_f32 v20, v28, v25, -v18
	v_fmac_f32_e32 v20, v28, v26
	v_sub_f32_e32 v19, v19, v17
	v_add_f32_e32 v25, v16, v19
	v_add_f32_e32 v16, v18, v20
	v_sub_f32_e32 v19, v17, v16
	v_pk_add_f32 v[22:23], v[16:17], v[18:19] neg_lo:[0,1] neg_hi:[0,1]
	v_mov_b32_e32 v21, v16
	v_pk_add_f32 v[16:17], v[22:23], v[20:21] neg_lo:[0,1] neg_hi:[0,1]
	s_nop 0
	v_add_f32_e32 v17, v25, v17
	v_add_f32_e32 v16, v16, v17
	v_add_f32_e32 v17, v29, v28
	v_add_f32_e32 v16, v19, v16
	v_sub_f32_e32 v18, v17, v29
	v_mul_f32_e32 v16, v27, v16
	v_sub_f32_e32 v18, v28, v18
	v_add_f32_e32 v18, v18, v16
	v_add_f32_e32 v20, v17, v18
	v_mul_f32_e32 v21, v20, v20
	v_fmamk_f32 v16, v21, 0x3e9b6dac, v54
	v_fmaak_f32 v41, v21, v16, 0x3f2aaada
	v_cvt_f32_i32_e32 v16, v24
	v_sub_f32_e32 v17, v20, v17
	v_sub_f32_e32 v17, v18, v17
	v_ldexp_f32 v22, v17, 1
	v_mul_f32_e32 v17, v20, v21
	v_ldexp_f32 v19, v20, 1
	v_pk_mul_f32 v[20:21], v[16:17], v[40:41]
	s_nop 0
	v_fma_f32 v18, v16, s52, -v20
	v_fmac_f32_e32 v18, 0xb102e308, v16
	v_pk_add_f32 v[16:17], v[20:21], v[18:19]
	s_nop 0
	v_sub_f32_e32 v19, v17, v19
	v_sub_f32_e32 v19, v21, v19
	v_add_f32_e32 v23, v22, v19
	v_mov_b32_e32 v22, v20
	v_pk_add_f32 v[20:21], v[16:17], v[20:21] neg_lo:[0,1] neg_hi:[0,1]
	v_pk_add_f32 v[24:25], v[16:17], v[22:23]
	v_mov_b32_e32 v19, v16
	v_mov_b32_e32 v21, v25
	v_pk_add_f32 v[26:27], v[18:19], v[20:21] neg_lo:[0,1] neg_hi:[0,1]
	v_pk_add_f32 v[18:19], v[18:19], v[20:21]
	v_mov_b32_e32 v22, v23
	v_pk_add_f32 v[20:21], v[18:19], v[16:17] op_sel:[1,0] op_sel_hi:[0,1] neg_lo:[0,1] neg_hi:[0,1]
	v_pk_add_f32 v[28:29], v[24:25], v[20:21] op_sel_hi:[1,0] neg_lo:[0,1] neg_hi:[0,1]
	v_mov_b32_e32 v24, v25
	v_mov_b32_e32 v25, v19
	v_pk_mov_b32 v[20:21], v[16:17], v[20:21] op_sel:[1,0]
	v_mov_b32_e32 v23, v16
	v_pk_add_f32 v[20:21], v[24:25], v[20:21] neg_lo:[0,1] neg_hi:[0,1]
	v_mov_b32_e32 v28, v26
	v_pk_add_f32 v[16:17], v[22:23], v[20:21] neg_lo:[0,1] neg_hi:[0,1]
	v_mov_b32_e32 v27, v19
	v_pk_add_f32 v[20:21], v[28:29], v[16:17]
	s_nop 0
	v_pk_add_f32 v[22:23], v[20:21], v[20:21] op_sel:[0,1] op_sel_hi:[1,0]
	s_nop 0
	v_pk_add_f32 v[18:19], v[18:19], v[22:23] op_sel:[1,0] op_sel_hi:[0,1]
	v_mov_b32_e32 v21, v18
	v_pk_add_f32 v[24:25], v[20:21], v[26:27] neg_lo:[0,1] neg_hi:[0,1]
	v_mov_b32_e32 v17, v22
	v_sub_f32_e32 v19, v20, v24
	v_pk_add_f32 v[16:17], v[16:17], v[24:25] neg_lo:[0,1] neg_hi:[0,1]
	v_sub_f32_e32 v19, v26, v19
	v_add_f32_e32 v16, v16, v19
	v_add_f32_e32 v16, v16, v17
	v_add_f32_e32 v16, v18, v16
	v_cndmask_b32_e64 v16, v55, v16, s[28:29]
	v_cmp_ngt_f32_e64 s[28:29], -1.0, v30
	s_nop 1
	v_cndmask_b32_e64 v16, v56, v16, s[28:29]
	v_cmp_neq_f32_e64 s[28:29], -1.0, v30
	s_nop 1
	v_cndmask_b32_e64 v16, v57, v16, s[28:29]
	v_cmp_lt_f32_e64 s[28:29], |v30|, s54
	s_nop 1
	v_cndmask_b32_e64 v16, v16, v30, s[28:29]
	s_branch .LBB0_47

.LBB0_1265:
	s_cmp_lt_i32 s68, 9
	s_cselect_b64 s[0:1], -1, 0
	s_and_b64 s[0:1], s[0:1], s[4:5]
	s_andn2_b64 vcc, exec, s[0:1]
	s_cbranch_vccnz .LBB0_1271
	s_lshl_b32 s0, s97, 3
	s_add_i32 s2, s2, s0
	s_cmpk_gt_i32 s2, 0x41ff
	s_cbranch_scc1 .LBB0_1271
	s_load_dwordx4 s[4:7], s[44:45], 0x98
	s_waitcnt vmcnt(0)
	v_lshlrev_b32_e32 v48, 4, v192
	v_mov_b32_e32 v49, 0
	v_mov_b32_e32 v50, 0x3727c5ac
	v_mov_b32_e32 v56, 0x1f1ee000
	s_lshl_b32 s0, s96, 3
	s_mov_b32 s1, 0x800000
	s_waitcnt lgkmcnt(0)
	global_load_dwordx4 v[0:3], v48, s[4:5]
	global_load_dwordx4 v[4:7], v48, s[4:5] offset:1024
	global_load_dwordx4 v[8:11], v48, s[4:5] offset:2048
	global_load_dwordx4 v[12:15], v48, s[4:5] offset:3072
.Lp8_batch:
	s_mov_b32 s3, s2
	s_mov_b32 s16, 0
	s_cmpk_gt_i32 s3, 0x41ff
	s_cbranch_scc1 .Lp8_issued
	s_lshl_b32 s10, s3, 2
	s_add_u32 s10, s40, s10
	s_addc_u32 s11, s41, 0
	s_lshl_b32 s12, s3, 12
	s_add_u32 s12, s6, s12
	s_addc_u32 s13, s7, 0
	global_load_dword v200, v56, s[10:11]
	global_load_dwordx4 v[64:67], v48, s[12:13] nt
	global_load_dwordx4 v[68:71], v48, s[12:13] offset:1024 nt
	global_load_dwordx4 v[72:75], v48, s[12:13] offset:2048 nt
	global_load_dwordx4 v[76:79], v48, s[12:13] offset:3072 nt
	s_add_i32 s3, s3, s0
	s_add_i32 s16, s16, 1
	s_cmpk_gt_i32 s3, 0x41ff
	s_cbranch_scc1 .Lp8_issued
	s_lshl_b32 s10, s3, 2
	s_add_u32 s10, s40, s10
	s_addc_u32 s11, s41, 0
	s_lshl_b32 s12, s3, 12
	s_add_u32 s12, s6, s12
	s_addc_u32 s13, s7, 0
	global_load_dword v201, v56, s[10:11]
	global_load_dwordx4 v[80:83], v48, s[12:13] nt
	global_load_dwordx4 v[84:87], v48, s[12:13] offset:1024 nt
	global_load_dwordx4 v[88:91], v48, s[12:13] offset:2048 nt
	global_load_dwordx4 v[92:95], v48, s[12:13] offset:3072 nt
	s_add_i32 s3, s3, s0
	s_add_i32 s16, s16, 1
	s_cmpk_gt_i32 s3, 0x41ff
	s_cbranch_scc1 .Lp8_issued
	s_lshl_b32 s10, s3, 2
	s_add_u32 s10, s40, s10
	s_addc_u32 s11, s41, 0
	s_lshl_b32 s12, s3, 12
	s_add_u32 s12, s6, s12
	s_addc_u32 s13, s7, 0
	global_load_dword v202, v56, s[10:11]
	global_load_dwordx4 v[96:99], v48, s[12:13] nt
	global_load_dwordx4 v[100:103], v48, s[12:13] offset:1024 nt
	global_load_dwordx4 v[104:107], v48, s[12:13] offset:2048 nt
	global_load_dwordx4 v[108:111], v48, s[12:13] offset:3072 nt
	s_add_i32 s3, s3, s0
	s_add_i32 s16, s16, 1
	s_cmpk_gt_i32 s3, 0x41ff
	s_cbranch_scc1 .Lp8_issued
	s_lshl_b32 s10, s3, 2
	s_add_u32 s10, s40, s10
	s_addc_u32 s11, s41, 0
	s_lshl_b32 s12, s3, 12
	s_add_u32 s12, s6, s12
	s_addc_u32 s13, s7, 0
	global_load_dword v203, v56, s[10:11]
	global_load_dwordx4 v[112:115], v48, s[12:13] nt
	global_load_dwordx4 v[116:119], v48, s[12:13] offset:1024 nt
	global_load_dwordx4 v[120:123], v48, s[12:13] offset:2048 nt
	global_load_dwordx4 v[124:127], v48, s[12:13] offset:3072 nt
	s_add_i32 s3, s3, s0
	s_add_i32 s16, s16, 1
	s_cmpk_gt_i32 s3, 0x41ff
	s_cbranch_scc1 .Lp8_issued
	s_lshl_b32 s10, s3, 2
	s_add_u32 s10, s40, s10
	s_addc_u32 s11, s41, 0
	s_lshl_b32 s12, s3, 12
	s_add_u32 s12, s6, s12
	s_addc_u32 s13, s7, 0
	global_load_dword v204, v56, s[10:11]
	global_load_dwordx4 v[128:131], v48, s[12:13] nt
	global_load_dwordx4 v[132:135], v48, s[12:13] offset:1024 nt
	global_load_dwordx4 v[136:139], v48, s[12:13] offset:2048 nt
	global_load_dwordx4 v[140:143], v48, s[12:13] offset:3072 nt
	s_add_i32 s3, s3, s0
	s_add_i32 s16, s16, 1
	s_cmpk_gt_i32 s3, 0x41ff
	s_cbranch_scc1 .Lp8_issued
	s_lshl_b32 s10, s3, 2
	s_add_u32 s10, s40, s10
	s_addc_u32 s11, s41, 0
	s_lshl_b32 s12, s3, 12
	s_add_u32 s12, s6, s12
	s_addc_u32 s13, s7, 0
	global_load_dword v205, v56, s[10:11]
	global_load_dwordx4 v[144:147], v48, s[12:13] nt
	global_load_dwordx4 v[148:151], v48, s[12:13] offset:1024 nt
	global_load_dwordx4 v[152:155], v48, s[12:13] offset:2048 nt
	global_load_dwordx4 v[156:159], v48, s[12:13] offset:3072 nt
	s_add_i32 s3, s3, s0
	s_add_i32 s16, s16, 1
	s_cmpk_gt_i32 s3, 0x41ff
	s_cbranch_scc1 .Lp8_issued
	s_lshl_b32 s10, s3, 2
	s_add_u32 s10, s40, s10
	s_addc_u32 s11, s41, 0
	s_lshl_b32 s12, s3, 12
	s_add_u32 s12, s6, s12
	s_addc_u32 s13, s7, 0
	global_load_dword v206, v56, s[10:11]
	global_load_dwordx4 v[160:163], v48, s[12:13] nt
	global_load_dwordx4 v[164:167], v48, s[12:13] offset:1024 nt
	global_load_dwordx4 v[168:171], v48, s[12:13] offset:2048 nt
	global_load_dwordx4 v[172:175], v48, s[12:13] offset:3072 nt
	s_add_i32 s3, s3, s0
	s_add_i32 s16, s16, 1
	s_cmpk_gt_i32 s3, 0x41ff
	s_cbranch_scc1 .Lp8_issued
	s_lshl_b32 s10, s3, 2
	s_add_u32 s10, s40, s10
	s_addc_u32 s11, s41, 0
	s_lshl_b32 s12, s3, 12
	s_add_u32 s12, s6, s12
	s_addc_u32 s13, s7, 0
	global_load_dword v207, v56, s[10:11]
	global_load_dwordx4 v[176:179], v48, s[12:13] nt
	global_load_dwordx4 v[180:183], v48, s[12:13] offset:1024 nt
	global_load_dwordx4 v[184:187], v48, s[12:13] offset:2048 nt
	global_load_dwordx4 v[188:191], v48, s[12:13] offset:3072 nt
	s_add_i32 s3, s3, s0
	s_add_i32 s16, s16, 1
.Lp8_issued:
	s_cmp_eq_u32 s16, 8
	s_cbranch_scc1 .Lp8_full
	s_waitcnt vmcnt(0)
.Lp8_full:
	s_mov_b32 s3, s2
	s_cmp_le_u32 s16, 0
	s_cbranch_scc1 .Lp8_bdone
	s_waitcnt vmcnt(35)
	v_fmamk_f32 v52, v200, 0x3a800000, v50
	v_mul_f32_e32 v53, 0x4b800000, v52
	v_cmp_gt_f32_e32 vcc, s1, v52
	s_nop 1
	v_cndmask_b32_e32 v52, v52, v53, vcc
	v_rsq_f32_e32 v54, v52
	s_lshl_b32 s12, s3, 12
	s_add_u32 s12, s6, s12
	s_addc_u32 s13, s7, 0
	v_mul_f32_e32 v55, 0x45800000, v54
	v_cndmask_b32_e32 v54, v54, v55, vcc
	v_pk_mul_f32 v[64:65], v[64:65], v[54:55] op_sel_hi:[1,0]
	v_pk_mul_f32 v[66:67], v[66:67], v[54:55] op_sel_hi:[1,0]
	v_pk_mul_f32 v[68:69], v[68:69], v[54:55] op_sel_hi:[1,0]
	v_pk_mul_f32 v[70:71], v[70:71], v[54:55] op_sel_hi:[1,0]
	v_pk_mul_f32 v[72:73], v[72:73], v[54:55] op_sel_hi:[1,0]
	v_pk_mul_f32 v[74:75], v[74:75], v[54:55] op_sel_hi:[1,0]
	v_pk_mul_f32 v[76:77], v[76:77], v[54:55] op_sel_hi:[1,0]
	v_pk_mul_f32 v[78:79], v[78:79], v[54:55] op_sel_hi:[1,0]
	v_pk_mul_f32 v[64:65], v[0:1], v[64:65]
	v_pk_mul_f32 v[66:67], v[2:3], v[66:67]
	v_pk_mul_f32 v[68:69], v[4:5], v[68:69]
	v_pk_mul_f32 v[70:71], v[6:7], v[70:71]
	v_pk_mul_f32 v[72:73], v[8:9], v[72:73]
	v_pk_mul_f32 v[74:75], v[10:11], v[74:75]
	v_pk_mul_f32 v[76:77], v[12:13], v[76:77]
	v_pk_mul_f32 v[78:79], v[14:15], v[78:79]
	global_store_dwordx4 v48, v[64:67], s[12:13] nt
	global_store_dwordx4 v48, v[68:71], s[12:13] offset:1024 nt
	global_store_dwordx4 v48, v[72:75], s[12:13] offset:2048 nt
	global_store_dwordx4 v48, v[76:79], s[12:13] offset:3072 nt
	s_add_i32 s3, s3, s0
	s_cmp_le_u32 s16, 1
	s_cbranch_scc1 .Lp8_bdone
	s_waitcnt vmcnt(34)
	v_fmamk_f32 v52, v201, 0x3a800000, v50
	v_mul_f32_e32 v53, 0x4b800000, v52
	v_cmp_gt_f32_e32 vcc, s1, v52
	s_nop 1
	v_cndmask_b32_e32 v52, v52, v53, vcc
	v_rsq_f32_e32 v54, v52
	s_lshl_b32 s12, s3, 12
	s_add_u32 s12, s6, s12
	s_addc_u32 s13, s7, 0
	v_mul_f32_e32 v55, 0x45800000, v54
	v_cndmask_b32_e32 v54, v54, v55, vcc
	v_pk_mul_f32 v[80:81], v[80:81], v[54:55] op_sel_hi:[1,0]
	v_pk_mul_f32 v[82:83], v[82:83], v[54:55] op_sel_hi:[1,0]
	v_pk_mul_f32 v[84:85], v[84:85], v[54:55] op_sel_hi:[1,0]
	v_pk_mul_f32 v[86:87], v[86:87], v[54:55] op_sel_hi:[1,0]
	v_pk_mul_f32 v[88:89], v[88:89], v[54:55] op_sel_hi:[1,0]
	v_pk_mul_f32 v[90:91], v[90:91], v[54:55] op_sel_hi:[1,0]
	v_pk_mul_f32 v[92:93], v[92:93], v[54:55] op_sel_hi:[1,0]
	v_pk_mul_f32 v[94:95], v[94:95], v[54:55] op_sel_hi:[1,0]
	v_pk_mul_f32 v[80:81], v[0:1], v[80:81]
	v_pk_mul_f32 v[82:83], v[2:3], v[82:83]
	v_pk_mul_f32 v[84:85], v[4:5], v[84:85]
	v_pk_mul_f32 v[86:87], v[6:7], v[86:87]
	v_pk_mul_f32 v[88:89], v[8:9], v[88:89]
	v_pk_mul_f32 v[90:91], v[10:11], v[90:91]
	v_pk_mul_f32 v[92:93], v[12:13], v[92:93]
	v_pk_mul_f32 v[94:95], v[14:15], v[94:95]
	global_store_dwordx4 v48, v[80:83], s[12:13] nt
	global_store_dwordx4 v48, v[84:87], s[12:13] offset:1024 nt
	global_store_dwordx4 v48, v[88:91], s[12:13] offset:2048 nt
	global_store_dwordx4 v48, v[92:95], s[12:13] offset:3072 nt
	s_add_i32 s3, s3, s0
	s_cmp_le_u32 s16, 2
	s_cbranch_scc1 .Lp8_bdone
	s_waitcnt vmcnt(33)
	v_fmamk_f32 v52, v202, 0x3a800000, v50
	v_mul_f32_e32 v53, 0x4b800000, v52
	v_cmp_gt_f32_e32 vcc, s1, v52
	s_nop 1
	v_cndmask_b32_e32 v52, v52, v53, vcc
	v_rsq_f32_e32 v54, v52
	s_lshl_b32 s12, s3, 12
	s_add_u32 s12, s6, s12
	s_addc_u32 s13, s7, 0
	v_mul_f32_e32 v55, 0x45800000, v54
	v_cndmask_b32_e32 v54, v54, v55, vcc
	v_pk_mul_f32 v[96:97], v[96:97], v[54:55] op_sel_hi:[1,0]
	v_pk_mul_f32 v[98:99], v[98:99], v[54:55] op_sel_hi:[1,0]
	v_pk_mul_f32 v[100:101], v[100:101], v[54:55] op_sel_hi:[1,0]
	v_pk_mul_f32 v[102:103], v[102:103], v[54:55] op_sel_hi:[1,0]
	v_pk_mul_f32 v[104:105], v[104:105], v[54:55] op_sel_hi:[1,0]
	v_pk_mul_f32 v[106:107], v[106:107], v[54:55] op_sel_hi:[1,0]
	v_pk_mul_f32 v[108:109], v[108:109], v[54:55] op_sel_hi:[1,0]
	v_pk_mul_f32 v[110:111], v[110:111], v[54:55] op_sel_hi:[1,0]
	v_pk_mul_f32 v[96:97], v[0:1], v[96:97]
	v_pk_mul_f32 v[98:99], v[2:3], v[98:99]
	v_pk_mul_f32 v[100:101], v[4:5], v[100:101]
	v_pk_mul_f32 v[102:103], v[6:7], v[102:103]
	v_pk_mul_f32 v[104:105], v[8:9], v[104:105]
	v_pk_mul_f32 v[106:107], v[10:11], v[106:107]
	v_pk_mul_f32 v[108:109], v[12:13], v[108:109]
	v_pk_mul_f32 v[110:111], v[14:15], v[110:111]
	global_store_dwordx4 v48, v[96:99], s[12:13] nt
	global_store_dwordx4 v48, v[100:103], s[12:13] offset:1024 nt
	global_store_dwordx4 v48, v[104:107], s[12:13] offset:2048 nt
	global_store_dwordx4 v48, v[108:111], s[12:13] offset:3072 nt
	s_add_i32 s3, s3, s0
	s_cmp_le_u32 s16, 3
	s_cbranch_scc1 .Lp8_bdone
	s_waitcnt vmcnt(32)
	v_fmamk_f32 v52, v203, 0x3a800000, v50
	v_mul_f32_e32 v53, 0x4b800000, v52
	v_cmp_gt_f32_e32 vcc, s1, v52
	s_nop 1
	v_cndmask_b32_e32 v52, v52, v53, vcc
	v_rsq_f32_e32 v54, v52
	s_lshl_b32 s12, s3, 12
	s_add_u32 s12, s6, s12
	s_addc_u32 s13, s7, 0
	v_mul_f32_e32 v55, 0x45800000, v54
	v_cndmask_b32_e32 v54, v54, v55, vcc
	v_pk_mul_f32 v[112:113], v[112:113], v[54:55] op_sel_hi:[1,0]
	v_pk_mul_f32 v[114:115], v[114:115], v[54:55] op_sel_hi:[1,0]
	v_pk_mul_f32 v[116:117], v[116:117], v[54:55] op_sel_hi:[1,0]
	v_pk_mul_f32 v[118:119], v[118:119], v[54:55] op_sel_hi:[1,0]
	v_pk_mul_f32 v[120:121], v[120:121], v[54:55] op_sel_hi:[1,0]
	v_pk_mul_f32 v[122:123], v[122:123], v[54:55] op_sel_hi:[1,0]
	v_pk_mul_f32 v[124:125], v[124:125], v[54:55] op_sel_hi:[1,0]
	v_pk_mul_f32 v[126:127], v[126:127], v[54:55] op_sel_hi:[1,0]
	v_pk_mul_f32 v[112:113], v[0:1], v[112:113]
	v_pk_mul_f32 v[114:115], v[2:3], v[114:115]
	v_pk_mul_f32 v[116:117], v[4:5], v[116:117]
	v_pk_mul_f32 v[118:119], v[6:7], v[118:119]
	v_pk_mul_f32 v[120:121], v[8:9], v[120:121]
	v_pk_mul_f32 v[122:123], v[10:11], v[122:123]
	v_pk_mul_f32 v[124:125], v[12:13], v[124:125]
	v_pk_mul_f32 v[126:127], v[14:15], v[126:127]
	global_store_dwordx4 v48, v[112:115], s[12:13] nt
	global_store_dwordx4 v48, v[116:119], s[12:13] offset:1024 nt
	global_store_dwordx4 v48, v[120:123], s[12:13] offset:2048 nt
	global_store_dwordx4 v48, v[124:127], s[12:13] offset:3072 nt
	s_add_i32 s3, s3, s0
	s_cmp_le_u32 s16, 4
	s_cbranch_scc1 .Lp8_bdone
	s_waitcnt vmcnt(31)
	v_fmamk_f32 v52, v204, 0x3a800000, v50
	v_mul_f32_e32 v53, 0x4b800000, v52
	v_cmp_gt_f32_e32 vcc, s1, v52
	s_nop 1
	v_cndmask_b32_e32 v52, v52, v53, vcc
	v_rsq_f32_e32 v54, v52
	s_lshl_b32 s12, s3, 12
	s_add_u32 s12, s6, s12
	s_addc_u32 s13, s7, 0
	v_mul_f32_e32 v55, 0x45800000, v54
	v_cndmask_b32_e32 v54, v54, v55, vcc
	v_pk_mul_f32 v[128:129], v[128:129], v[54:55] op_sel_hi:[1,0]
	v_pk_mul_f32 v[130:131], v[130:131], v[54:55] op_sel_hi:[1,0]
	v_pk_mul_f32 v[132:133], v[132:133], v[54:55] op_sel_hi:[1,0]
	v_pk_mul_f32 v[134:135], v[134:135], v[54:55] op_sel_hi:[1,0]
	v_pk_mul_f32 v[136:137], v[136:137], v[54:55] op_sel_hi:[1,0]
	v_pk_mul_f32 v[138:139], v[138:139], v[54:55] op_sel_hi:[1,0]
	v_pk_mul_f32 v[140:141], v[140:141], v[54:55] op_sel_hi:[1,0]
	v_pk_mul_f32 v[142:143], v[142:143], v[54:55] op_sel_hi:[1,0]
	v_pk_mul_f32 v[128:129], v[0:1], v[128:129]
	v_pk_mul_f32 v[130:131], v[2:3], v[130:131]
	v_pk_mul_f32 v[132:133], v[4:5], v[132:133]
	v_pk_mul_f32 v[134:135], v[6:7], v[134:135]
	v_pk_mul_f32 v[136:137], v[8:9], v[136:137]
	v_pk_mul_f32 v[138:139], v[10:11], v[138:139]
	v_pk_mul_f32 v[140:141], v[12:13], v[140:141]
	v_pk_mul_f32 v[142:143], v[14:15], v[142:143]
	global_store_dwordx4 v48, v[128:131], s[12:13] nt
	global_store_dwordx4 v48, v[132:135], s[12:13] offset:1024 nt
	global_store_dwordx4 v48, v[136:139], s[12:13] offset:2048 nt
	global_store_dwordx4 v48, v[140:143], s[12:13] offset:3072 nt
	s_add_i32 s3, s3, s0
	s_cmp_le_u32 s16, 5
	s_cbranch_scc1 .Lp8_bdone
	s_waitcnt vmcnt(30)
	v_fmamk_f32 v52, v205, 0x3a800000, v50
	v_mul_f32_e32 v53, 0x4b800000, v52
	v_cmp_gt_f32_e32 vcc, s1, v52
	s_nop 1
	v_cndmask_b32_e32 v52, v52, v53, vcc
	v_rsq_f32_e32 v54, v52
	s_lshl_b32 s12, s3, 12
	s_add_u32 s12, s6, s12
	s_addc_u32 s13, s7, 0
	v_mul_f32_e32 v55, 0x45800000, v54
	v_cndmask_b32_e32 v54, v54, v55, vcc
	v_pk_mul_f32 v[144:145], v[144:145], v[54:55] op_sel_hi:[1,0]
	v_pk_mul_f32 v[146:147], v[146:147], v[54:55] op_sel_hi:[1,0]
	v_pk_mul_f32 v[148:149], v[148:149], v[54:55] op_sel_hi:[1,0]
	v_pk_mul_f32 v[150:151], v[150:151], v[54:55] op_sel_hi:[1,0]
	v_pk_mul_f32 v[152:153], v[152:153], v[54:55] op_sel_hi:[1,0]
	v_pk_mul_f32 v[154:155], v[154:155], v[54:55] op_sel_hi:[1,0]
	v_pk_mul_f32 v[156:157], v[156:157], v[54:55] op_sel_hi:[1,0]
	v_pk_mul_f32 v[158:159], v[158:159], v[54:55] op_sel_hi:[1,0]
	v_pk_mul_f32 v[144:145], v[0:1], v[144:145]
	v_pk_mul_f32 v[146:147], v[2:3], v[146:147]
	v_pk_mul_f32 v[148:149], v[4:5], v[148:149]
	v_pk_mul_f32 v[150:151], v[6:7], v[150:151]
	v_pk_mul_f32 v[152:153], v[8:9], v[152:153]
	v_pk_mul_f32 v[154:155], v[10:11], v[154:155]
	v_pk_mul_f32 v[156:157], v[12:13], v[156:157]
	v_pk_mul_f32 v[158:159], v[14:15], v[158:159]
	global_store_dwordx4 v48, v[144:147], s[12:13] nt
	global_store_dwordx4 v48, v[148:151], s[12:13] offset:1024 nt
	global_store_dwordx4 v48, v[152:155], s[12:13] offset:2048 nt
	global_store_dwordx4 v48, v[156:159], s[12:13] offset:3072 nt
	s_add_i32 s3, s3, s0
	s_cmp_le_u32 s16, 6
	s_cbranch_scc1 .Lp8_bdone
	s_waitcnt vmcnt(29)
	v_fmamk_f32 v52, v206, 0x3a800000, v50
	v_mul_f32_e32 v53, 0x4b800000, v52
	v_cmp_gt_f32_e32 vcc, s1, v52
	s_nop 1
	v_cndmask_b32_e32 v52, v52, v53, vcc
	v_rsq_f32_e32 v54, v52
	s_lshl_b32 s12, s3, 12
	s_add_u32 s12, s6, s12
	s_addc_u32 s13, s7, 0
	v_mul_f32_e32 v55, 0x45800000, v54
	v_cndmask_b32_e32 v54, v54, v55, vcc
	v_pk_mul_f32 v[160:161], v[160:161], v[54:55] op_sel_hi:[1,0]
	v_pk_mul_f32 v[162:163], v[162:163], v[54:55] op_sel_hi:[1,0]
	v_pk_mul_f32 v[164:165], v[164:165], v[54:55] op_sel_hi:[1,0]
	v_pk_mul_f32 v[166:167], v[166:167], v[54:55] op_sel_hi:[1,0]
	v_pk_mul_f32 v[168:169], v[168:169], v[54:55] op_sel_hi:[1,0]
	v_pk_mul_f32 v[170:171], v[170:171], v[54:55] op_sel_hi:[1,0]
	v_pk_mul_f32 v[172:173], v[172:173], v[54:55] op_sel_hi:[1,0]
	v_pk_mul_f32 v[174:175], v[174:175], v[54:55] op_sel_hi:[1,0]
	v_pk_mul_f32 v[160:161], v[0:1], v[160:161]
	v_pk_mul_f32 v[162:163], v[2:3], v[162:163]
	v_pk_mul_f32 v[164:165], v[4:5], v[164:165]
	v_pk_mul_f32 v[166:167], v[6:7], v[166:167]
	v_pk_mul_f32 v[168:169], v[8:9], v[168:169]
	v_pk_mul_f32 v[170:171], v[10:11], v[170:171]
	v_pk_mul_f32 v[172:173], v[12:13], v[172:173]
	v_pk_mul_f32 v[174:175], v[14:15], v[174:175]
	global_store_dwordx4 v48, v[160:163], s[12:13] nt
	global_store_dwordx4 v48, v[164:167], s[12:13] offset:1024 nt
	global_store_dwordx4 v48, v[168:171], s[12:13] offset:2048 nt
	global_store_dwordx4 v48, v[172:175], s[12:13] offset:3072 nt
	s_add_i32 s3, s3, s0
	s_cmp_le_u32 s16, 7
	s_cbranch_scc1 .Lp8_bdone
	s_waitcnt vmcnt(28)
	v_fmamk_f32 v52, v207, 0x3a800000, v50
	v_mul_f32_e32 v53, 0x4b800000, v52
	v_cmp_gt_f32_e32 vcc, s1, v52
	s_nop 1
	v_cndmask_b32_e32 v52, v52, v53, vcc
	v_rsq_f32_e32 v54, v52
	s_lshl_b32 s12, s3, 12
	s_add_u32 s12, s6, s12
	s_addc_u32 s13, s7, 0
	v_mul_f32_e32 v55, 0x45800000, v54
	v_cndmask_b32_e32 v54, v54, v55, vcc
	v_pk_mul_f32 v[176:177], v[176:177], v[54:55] op_sel_hi:[1,0]
	v_pk_mul_f32 v[178:179], v[178:179], v[54:55] op_sel_hi:[1,0]
	v_pk_mul_f32 v[180:181], v[180:181], v[54:55] op_sel_hi:[1,0]
	v_pk_mul_f32 v[182:183], v[182:183], v[54:55] op_sel_hi:[1,0]
	v_pk_mul_f32 v[184:185], v[184:185], v[54:55] op_sel_hi:[1,0]
	v_pk_mul_f32 v[186:187], v[186:187], v[54:55] op_sel_hi:[1,0]
	v_pk_mul_f32 v[188:189], v[188:189], v[54:55] op_sel_hi:[1,0]
	v_pk_mul_f32 v[190:191], v[190:191], v[54:55] op_sel_hi:[1,0]
	v_pk_mul_f32 v[176:177], v[0:1], v[176:177]
	v_pk_mul_f32 v[178:179], v[2:3], v[178:179]
	v_pk_mul_f32 v[180:181], v[4:5], v[180:181]
	v_pk_mul_f32 v[182:183], v[6:7], v[182:183]
	v_pk_mul_f32 v[184:185], v[8:9], v[184:185]
	v_pk_mul_f32 v[186:187], v[10:11], v[186:187]
	v_pk_mul_f32 v[188:189], v[12:13], v[188:189]
	v_pk_mul_f32 v[190:191], v[14:15], v[190:191]
	global_store_dwordx4 v48, v[176:179], s[12:13] nt
	global_store_dwordx4 v48, v[180:183], s[12:13] offset:1024 nt
	global_store_dwordx4 v48, v[184:187], s[12:13] offset:2048 nt
	global_store_dwordx4 v48, v[188:191], s[12:13] offset:3072 nt
	s_add_i32 s3, s3, s0
.Lp8_bdone:
	s_lshl_b32 s3, s0, 3
	s_add_i32 s2, s2, s3
	s_cmpk_gt_i32 s2, 0x41ff
	s_cbranch_scc0 .Lp8_batch
